# k11 + grid barrier: each workgroup's cache invalidate issued at its arrival (overlaps the wait) instead of after the release
# speedup vs baseline: 1.0046x; 1.0046x over previous
.LBB0_463:
	s_mov_b64 s[8:9], exec
	v_readlane_b32 s3, v238, 4
	s_lshl_b32 s3, s3, 8
	v_mbcnt_lo_u32_b32 v2, s8, 0
	s_add_u32 s6, s42, s3
	v_mbcnt_hi_u32_b32 v2, s9, v2
	s_addc_u32 s7, s43, 0
	v_cmp_eq_u32_e32 vcc, 0, v2
	s_and_saveexec_b64 s[12:13], vcc
	s_cbranch_execz .LBB0_465
	s_bcnt1_i32_b64 s3, s[8:9]
	v_mov_b32_e32 v4, 0x1000
	v_mov_b32_e32 v5, s3
	buffer_inv sc1
	global_atomic_add v4, v4, v5, s[6:7] offset:1024 sc0

.LBB0_478:
	s_or_b64 exec, exec, s[12:13]
	s_waitcnt vmcnt(0)
	s_waitcnt vmcnt(0)

.LBB0_496:
	s_or_b64 exec, exec, s[8:9]
	s_mov_b64 s[8:9], exec
	v_mbcnt_lo_u32_b32 v1, s8, 0
	v_mbcnt_hi_u32_b32 v1, s9, v1
	v_cmp_eq_u32_e32 vcc, 0, v1
	s_waitcnt vmcnt(0)
	s_and_saveexec_b64 s[12:13], vcc
	s_cbranch_execz .LBB0_498
	s_bcnt1_i32_b64 s3, s[8:9]
	v_mov_b32_e32 v1, 0x2000
	v_mov_b32_e32 v2, s3

.LBB0_2906:
	s_mov_b64 s[8:9], exec
	v_readlane_b32 s3, v238, 4
	s_lshl_b32 s3, s3, 8
	v_mbcnt_lo_u32_b32 v2, s8, 0
	s_add_u32 s4, s42, s3
	v_mbcnt_hi_u32_b32 v2, s9, v2
	s_addc_u32 s5, s43, 0
	v_cmp_eq_u32_e32 vcc, 0, v2
	s_and_saveexec_b64 s[12:13], vcc
	s_cbranch_execz .LBB0_2908
	s_bcnt1_i32_b64 s3, s[8:9]
	v_mov_b32_e32 v4, 0x1000
	v_mov_b32_e32 v5, s3
	buffer_inv sc1
	global_atomic_add v4, v4, v5, s[4:5] offset:1024 sc0

.LBB0_4156:
	s_mov_b64 s[8:9], exec
	v_readlane_b32 s3, v238, 4
	s_lshl_b32 s3, s3, 8
	v_mbcnt_lo_u32_b32 v2, s8, 0
	s_add_u32 s6, s42, s3
	v_mbcnt_hi_u32_b32 v2, s9, v2
	s_addc_u32 s7, s43, 0
	v_cmp_eq_u32_e32 vcc, 0, v2
	s_and_saveexec_b64 s[10:11], vcc
	s_cbranch_execz .LBB0_4158
	s_bcnt1_i32_b64 s3, s[8:9]
	v_mov_b32_e32 v4, 0x1000
	v_mov_b32_e32 v5, s3
	buffer_inv sc1
	global_atomic_add v4, v4, v5, s[6:7] offset:1024 sc0

.LBB0_4171:
	s_or_b64 exec, exec, s[10:11]
	s_waitcnt vmcnt(0)
	s_waitcnt vmcnt(0)

.LBB0_4189:
	s_or_b64 exec, exec, s[8:9]
	s_mov_b64 s[8:9], exec
	v_mbcnt_lo_u32_b32 v1, s8, 0
	v_mbcnt_hi_u32_b32 v1, s9, v1
	v_cmp_eq_u32_e32 vcc, 0, v1
	s_waitcnt vmcnt(0)
	s_and_saveexec_b64 s[10:11], vcc
	s_cbranch_execz .LBB0_4191
	s_bcnt1_i32_b64 s3, s[8:9]
	v_mov_b32_e32 v1, 0x2000
	v_mov_b32_e32 v2, s3
